# v22
# speedup vs baseline: 1.0026x; 1.0026x over previous
;     MI bool next(int i, Unit& u) const { return o.next(i, u); }
;     MI const char* aptr(const Unit& u) const { return (u.pn >= 8 && u.pn < 12) ? w + (size_t)u.pn * 256 * DM * 2 : hx + (size_t)u.pm * 256 * DM * 2; }
;     MI const char* bptr(const Unit& u) const { return (u.pn >= 8 && u.pn < 12) ? hx + (size_t)u.pm * 256 * DM * 2 : w + (size_t)u.pn * 256 * DM * 2; }
;     MI bool next(int i, Unit& u) const { return o.next(i, u); }
; template <bool PERM, class Epi, class Sched>
; __device__ __forceinline__ void gemm_phase(LAS unsigned char* lds, const int K, const Sched& S, const Epi& E, const int wid0) {
;     ...
;         const bool has_next = S.next(ui + 1, nxt);
;         const char* nA = has_next ? S.aptr(nxt) : cA; const char* nB = has_next ? S.bptr(nxt) : cB;
;     ...
; #pragma unroll
;         for (int a = 0; a < 2; ++a)
; #pragma unroll
;             for (int b = 0; b < 2; ++b)
; #pragma unroll
;                 for (int m = 0; m < 4; ++m)
; #pragma unroll
;                     for (int n = 0; n < 2; ++n) acc[a][b][m][n] = (f32x4){0.f, 0.f, 0.f, 0.f};
.LBB0_246:
	s_and_b64 s[16:17], s[22:23], exec
	s_cselect_b32 s16, s76, s50
	s_ashr_i32 s17, s16, 31
	s_lshl_b64 s[16:17], s[16:17], 20
	s_and_b64 s[22:23], s[22:23], exec
	v_readlane_b32 s22, v255, 1
	v_readlane_b32 s23, v255, 2
	s_cselect_b32 s22, s86, s22
	s_cselect_b32 s18, s87, s23
	s_add_u32 s22, s22, s16
	s_addc_u32 s23, s18, s17
	s_and_b64 s[8:9], s[8:9], exec
	s_cselect_b32 s18, s23, s81
	s_cselect_b32 s46, s22, s80
	s_add_u32 s8, s68, 0x80080
	s_addc_u32 s9, s69, 0
	s_add_u32 s48, s80, 0x100
	v_mov_b32_e32 v0, 0
	s_addc_u32 s77, s81, 0
	s_mov_b32 vcc_lo, -2
	v_mov_b32_e32 v1, v0
	v_mov_b64_e32 v[2:3], v[0:1]
	v_mov_b64_e32 v[4:5], v[0:1]
	v_mov_b64_e32 v[6:7], v[0:1]
	v_mov_b64_e32 v[8:9], v[0:1]
	v_mov_b64_e32 v[10:11], v[0:1]
	v_mov_b64_e32 v[12:13], v[0:1]
	v_mov_b64_e32 v[14:15], v[0:1]
	v_mov_b64_e32 v[16:17], v[0:1]
	v_mov_b64_e32 v[18:19], v[0:1]
	v_mov_b64_e32 v[20:21], v[0:1]
	v_mov_b64_e32 v[22:23], v[0:1]
	v_mov_b64_e32 v[24:25], v[0:1]
	v_mov_b64_e32 v[26:27], v[0:1]
	v_mov_b64_e32 v[28:29], v[0:1]
	v_mov_b64_e32 v[30:31], v[0:1]
	v_mov_b64_e32 v[32:33], v[0:1]
	v_mov_b64_e32 v[34:35], v[0:1]
	v_mov_b64_e32 v[36:37], v[0:1]
	v_mov_b64_e32 v[38:39], v[0:1]
	v_mov_b64_e32 v[40:41], v[0:1]
	v_mov_b64_e32 v[42:43], v[0:1]
	v_mov_b64_e32 v[44:45], v[0:1]
	v_mov_b64_e32 v[46:47], v[0:1]
	v_mov_b64_e32 v[48:49], v[0:1]
	v_mov_b64_e32 v[50:51], v[0:1]
	v_mov_b64_e32 v[52:53], v[0:1]
	v_mov_b64_e32 v[54:55], v[0:1]
	v_mov_b64_e32 v[56:57], v[0:1]
	v_mov_b64_e32 v[58:59], v[0:1]
	v_mov_b64_e32 v[60:61], v[0:1]
	v_mov_b64_e32 v[62:63], v[0:1]
	v_mov_b64_e32 v[64:65], v[0:1]
	v_mov_b64_e32 v[66:67], v[0:1]
	v_mov_b64_e32 v[68:69], v[0:1]
	v_mov_b64_e32 v[70:71], v[0:1]
	v_mov_b64_e32 v[72:73], v[0:1]
	v_mov_b64_e32 v[74:75], v[0:1]
	v_mov_b64_e32 v[76:77], v[0:1]
	v_mov_b64_e32 v[78:79], v[0:1]
	v_mov_b64_e32 v[80:81], v[0:1]
	v_mov_b64_e32 v[82:83], v[0:1]
	v_mov_b64_e32 v[84:85], v[0:1]
	v_mov_b64_e32 v[86:87], v[0:1]
	v_mov_b64_e32 v[88:89], v[0:1]
	v_mov_b64_e32 v[90:91], v[0:1]
	v_mov_b64_e32 v[92:93], v[0:1]
	v_mov_b64_e32 v[94:95], v[0:1]
	v_mov_b64_e32 v[96:97], v[0:1]
	v_mov_b64_e32 v[98:99], v[0:1]
	v_mov_b64_e32 v[100:101], v[0:1]
	v_mov_b64_e32 v[102:103], v[0:1]
	v_mov_b64_e32 v[104:105], v[0:1]
	v_mov_b64_e32 v[106:107], v[0:1]
	v_mov_b64_e32 v[108:109], v[0:1]
	v_mov_b64_e32 v[110:111], v[0:1]
	v_mov_b64_e32 v[112:113], v[0:1]
	v_mov_b64_e32 v[114:115], v[0:1]
	v_mov_b64_e32 v[116:117], v[0:1]
	v_mov_b64_e32 v[118:119], v[0:1]
	v_mov_b64_e32 v[120:121], v[0:1]
	v_mov_b64_e32 v[122:123], v[0:1]
	v_mov_b64_e32 v[124:125], v[0:1]
	v_mov_b64_e32 v[126:127], v[0:1]

;     MI bool next(int i, Unit& u) const { return o.next(i, u); }
;     MI const char* aptr(const Unit& u) const { return (u.pn >= 8 && u.pn < 12) ? w + (size_t)u.pn * 256 * DM * 2 : hx + (size_t)u.pm * 256 * DM * 2; }
;     MI const char* bptr(const Unit& u) const { return (u.pn >= 8 && u.pn < 12) ? hx + (size_t)u.pm * 256 * DM * 2 : w + (size_t)u.pn * 256 * DM * 2; }
;     MI bool next(int i, Unit& u) const { return o.next(i, u); }
; template <bool PERM, class Epi, class Sched>
; __device__ __forceinline__ void gemm_phase(LAS unsigned char* lds, const int K, const Sched& S, const Epi& E, const int wid0) {
;     ...
;         const bool has_next = S.next(ui + 1, nxt);
;         const char* nA = has_next ? S.aptr(nxt) : cA; const char* nB = has_next ? S.bptr(nxt) : cB;
;     ...
; #pragma unroll
;         for (int a = 0; a < 2; ++a)
; #pragma unroll
;             for (int b = 0; b < 2; ++b)
; #pragma unroll
;                 for (int m = 0; m < 4; ++m)
; #pragma unroll
;                     for (int n = 0; n < 2; ++n) acc[a][b][m][n] = (f32x4){0.f, 0.f, 0.f, 0.f};
.LBB0_634:
	s_ashr_i32 s73, s72, 31
	s_lshl_b64 s[16:17], s[72:73], 19
	v_readlane_b32 s58, v253, 29
	v_readlane_b32 s59, v253, 30
	s_add_u32 s74, s58, s16
	s_addc_u32 s75, s59, s17
	s_and_b64 s[16:17], s[4:5], exec
	s_cselect_b32 s46, s75, s23
	s_cselect_b32 s48, s74, s22
	s_ashr_i32 s71, s70, 31
	s_lshl_b64 s[16:17], s[70:71], 19
	s_add_u32 s76, s60, s16
	v_readlane_b32 s16, v255, 7
	s_addc_u32 s77, s16, s17
	s_and_b64 s[16:17], s[4:5], exec
	s_cselect_b32 s71, s77, s7
	s_cselect_b32 s73, s76, s6
	s_add_u32 s82, s22, 0x40080
	s_addc_u32 s83, s23, 0
	s_add_u32 s79, s6, 0x100
	v_mov_b32_e32 v0, 0
	s_addc_u32 s81, s7, 0
	s_mov_b32 s92, -2
	v_mov_b32_e32 v1, v0
	v_mov_b64_e32 v[2:3], v[0:1]
	v_mov_b64_e32 v[4:5], v[0:1]
	v_mov_b64_e32 v[6:7], v[0:1]
	v_mov_b64_e32 v[8:9], v[0:1]
	v_mov_b64_e32 v[10:11], v[0:1]
	v_mov_b64_e32 v[12:13], v[0:1]
	v_mov_b64_e32 v[14:15], v[0:1]
	v_mov_b64_e32 v[16:17], v[0:1]
	v_mov_b64_e32 v[18:19], v[0:1]
	v_mov_b64_e32 v[20:21], v[0:1]
	v_mov_b64_e32 v[22:23], v[0:1]
	v_mov_b64_e32 v[24:25], v[0:1]
	v_mov_b64_e32 v[26:27], v[0:1]
	v_mov_b64_e32 v[28:29], v[0:1]
	v_mov_b64_e32 v[30:31], v[0:1]
	v_mov_b64_e32 v[32:33], v[0:1]
	v_mov_b64_e32 v[34:35], v[0:1]
	v_mov_b64_e32 v[36:37], v[0:1]
	v_mov_b64_e32 v[38:39], v[0:1]
	v_mov_b64_e32 v[40:41], v[0:1]
	v_mov_b64_e32 v[42:43], v[0:1]
	v_mov_b64_e32 v[44:45], v[0:1]
	v_mov_b64_e32 v[46:47], v[0:1]
	v_mov_b64_e32 v[48:49], v[0:1]
	v_mov_b64_e32 v[50:51], v[0:1]
	v_mov_b64_e32 v[52:53], v[0:1]
	v_mov_b64_e32 v[54:55], v[0:1]
	v_mov_b64_e32 v[56:57], v[0:1]
	v_mov_b64_e32 v[58:59], v[0:1]
	v_mov_b64_e32 v[60:61], v[0:1]
	v_mov_b64_e32 v[62:63], v[0:1]
	v_mov_b64_e32 v[64:65], v[0:1]
	v_mov_b64_e32 v[66:67], v[0:1]
	v_mov_b64_e32 v[68:69], v[0:1]
	v_mov_b64_e32 v[70:71], v[0:1]
	v_mov_b64_e32 v[72:73], v[0:1]
	v_mov_b64_e32 v[74:75], v[0:1]
	v_mov_b64_e32 v[76:77], v[0:1]
	v_mov_b64_e32 v[78:79], v[0:1]
	v_mov_b64_e32 v[80:81], v[0:1]
	v_mov_b64_e32 v[82:83], v[0:1]
	v_mov_b64_e32 v[84:85], v[0:1]
	v_mov_b64_e32 v[86:87], v[0:1]
	v_mov_b64_e32 v[88:89], v[0:1]
	v_mov_b64_e32 v[90:91], v[0:1]
	v_mov_b64_e32 v[92:93], v[0:1]
	v_mov_b64_e32 v[94:95], v[0:1]
	v_mov_b64_e32 v[96:97], v[0:1]
	v_mov_b64_e32 v[98:99], v[0:1]
	v_mov_b64_e32 v[100:101], v[0:1]
	v_mov_b64_e32 v[102:103], v[0:1]
	v_mov_b64_e32 v[104:105], v[0:1]
	v_mov_b64_e32 v[106:107], v[0:1]
	v_mov_b64_e32 v[108:109], v[0:1]
	v_mov_b64_e32 v[110:111], v[0:1]
	v_mov_b64_e32 v[112:113], v[0:1]
	v_mov_b64_e32 v[114:115], v[0:1]
	v_mov_b64_e32 v[116:117], v[0:1]
	v_mov_b64_e32 v[118:119], v[0:1]
	v_mov_b64_e32 v[120:121], v[0:1]
	v_mov_b64_e32 v[122:123], v[0:1]
	v_mov_b64_e32 v[124:125], v[0:1]
	v_mov_b64_e32 v[126:127], v[0:1]

;     MI bool next(int i, Unit& u) const { return o.next(i, u); }
;     MI const char* aptr(const Unit& u) const { return (u.pn >= 8 && u.pn < 12) ? w + (size_t)u.pn * 256 * DM * 2 : hx + (size_t)u.pm * 256 * DM * 2; }
;     MI const char* bptr(const Unit& u) const { return (u.pn >= 8 && u.pn < 12) ? hx + (size_t)u.pm * 256 * DM * 2 : w + (size_t)u.pn * 256 * DM * 2; }
;     MI bool next(int i, Unit& u) const { return o.next(i, u); }
; template <bool PERM, class Epi, class Sched>
; __device__ __forceinline__ void gemm_phase(LAS unsigned char* lds, const int K, const Sched& S, const Epi& E, const int wid0) {
;     ...
;         const bool has_next = S.next(ui + 1, nxt);
;         const char* nA = has_next ? S.aptr(nxt) : cA; const char* nB = has_next ? S.bptr(nxt) : cB;
;     ...
; #pragma unroll
;         for (int a = 0; a < 2; ++a)
; #pragma unroll
;             for (int b = 0; b < 2; ++b)
; #pragma unroll
;                 for (int m = 0; m < 4; ++m)
; #pragma unroll
;                     for (int n = 0; n < 2; ++n) acc[a][b][m][n] = (f32x4){0.f, 0.f, 0.f, 0.f};
.LBB0_650:
	s_ashr_i32 s73, s72, 31
	s_lshl_b64 s[16:17], s[72:73], 19
	s_add_u32 s74, s61, s16
	v_readlane_b32 s16, v253, 58
	s_addc_u32 s75, s16, s17
	s_and_b64 s[16:17], s[4:5], exec
	s_cselect_b32 s46, s75, s23
	s_cselect_b32 s48, s74, s22
	s_ashr_i32 s71, s70, 31
	s_lshl_b64 s[16:17], s[70:71], 19
	s_add_u32 s76, s60, s16
	v_readlane_b32 s16, v255, 9
	s_addc_u32 s77, s16, s17
	s_and_b64 s[16:17], s[4:5], exec
	s_cselect_b32 s71, s77, s7
	s_cselect_b32 s73, s76, s6
	s_add_u32 s82, s22, 0x40080
	s_addc_u32 s83, s23, 0
	s_add_u32 s79, s6, 0x100
	v_mov_b32_e32 v0, 0
	s_addc_u32 s81, s7, 0
	s_mov_b32 s92, -2
	v_mov_b32_e32 v1, v0
	v_mov_b64_e32 v[2:3], v[0:1]
	v_mov_b64_e32 v[4:5], v[0:1]
	v_mov_b64_e32 v[6:7], v[0:1]
	v_mov_b64_e32 v[8:9], v[0:1]
	v_mov_b64_e32 v[10:11], v[0:1]
	v_mov_b64_e32 v[12:13], v[0:1]
	v_mov_b64_e32 v[14:15], v[0:1]
	v_mov_b64_e32 v[16:17], v[0:1]
	v_mov_b64_e32 v[18:19], v[0:1]
	v_mov_b64_e32 v[20:21], v[0:1]
	v_mov_b64_e32 v[22:23], v[0:1]
	v_mov_b64_e32 v[24:25], v[0:1]
	v_mov_b64_e32 v[26:27], v[0:1]
	v_mov_b64_e32 v[28:29], v[0:1]
	v_mov_b64_e32 v[30:31], v[0:1]
	v_mov_b64_e32 v[32:33], v[0:1]
	v_mov_b64_e32 v[34:35], v[0:1]
	v_mov_b64_e32 v[36:37], v[0:1]
	v_mov_b64_e32 v[38:39], v[0:1]
	v_mov_b64_e32 v[40:41], v[0:1]
	v_mov_b64_e32 v[42:43], v[0:1]
	v_mov_b64_e32 v[44:45], v[0:1]
	v_mov_b64_e32 v[46:47], v[0:1]
	v_mov_b64_e32 v[48:49], v[0:1]
	v_mov_b64_e32 v[50:51], v[0:1]
	v_mov_b64_e32 v[52:53], v[0:1]
	v_mov_b64_e32 v[54:55], v[0:1]
	v_mov_b64_e32 v[56:57], v[0:1]
	v_mov_b64_e32 v[58:59], v[0:1]
	v_mov_b64_e32 v[60:61], v[0:1]
	v_mov_b64_e32 v[62:63], v[0:1]
	v_mov_b64_e32 v[64:65], v[0:1]
	v_mov_b64_e32 v[66:67], v[0:1]
	v_mov_b64_e32 v[68:69], v[0:1]
	v_mov_b64_e32 v[70:71], v[0:1]
	v_mov_b64_e32 v[72:73], v[0:1]
	v_mov_b64_e32 v[74:75], v[0:1]
	v_mov_b64_e32 v[76:77], v[0:1]
	v_mov_b64_e32 v[78:79], v[0:1]
	v_mov_b64_e32 v[80:81], v[0:1]
	v_mov_b64_e32 v[82:83], v[0:1]
	v_mov_b64_e32 v[84:85], v[0:1]
	v_mov_b64_e32 v[86:87], v[0:1]
	v_mov_b64_e32 v[88:89], v[0:1]
	v_mov_b64_e32 v[90:91], v[0:1]
	v_mov_b64_e32 v[92:93], v[0:1]
	v_mov_b64_e32 v[94:95], v[0:1]
	v_mov_b64_e32 v[96:97], v[0:1]
	v_mov_b64_e32 v[98:99], v[0:1]
	v_mov_b64_e32 v[100:101], v[0:1]
	v_mov_b64_e32 v[102:103], v[0:1]
	v_mov_b64_e32 v[104:105], v[0:1]
	v_mov_b64_e32 v[106:107], v[0:1]
	v_mov_b64_e32 v[108:109], v[0:1]
	v_mov_b64_e32 v[110:111], v[0:1]
	v_mov_b64_e32 v[112:113], v[0:1]
	v_mov_b64_e32 v[114:115], v[0:1]
	v_mov_b64_e32 v[116:117], v[0:1]
	v_mov_b64_e32 v[118:119], v[0:1]
	v_mov_b64_e32 v[120:121], v[0:1]
	v_mov_b64_e32 v[122:123], v[0:1]
	v_mov_b64_e32 v[124:125], v[0:1]
	v_mov_b64_e32 v[126:127], v[0:1]

;     MI bool next(int i, Unit& u) const { return o.next(i, u); }
;     MI const char* aptr(const Unit& u) const { return (u.pn >= 8 && u.pn < 12) ? w + (size_t)u.pn * 256 * DM * 2 : hx + (size_t)u.pm * 256 * DM * 2; }
;     MI const char* bptr(const Unit& u) const { return (u.pn >= 8 && u.pn < 12) ? hx + (size_t)u.pm * 256 * DM * 2 : w + (size_t)u.pn * 256 * DM * 2; }
;     MI bool next(int i, Unit& u) const { return o.next(i, u); }
; template <bool PERM, class Epi, class Sched>
; __device__ __forceinline__ void gemm_phase(LAS unsigned char* lds, const int K, const Sched& S, const Epi& E, const int wid0) {
;     ...
;         const bool has_next = S.next(ui + 1, nxt);
;         const char* nA = has_next ? S.aptr(nxt) : cA; const char* nB = has_next ? S.bptr(nxt) : cB;
;         for (int t = 0; t < nt; t += 2) {
;             const bool last = (t == nt - 2);
;             const char* a1 = cA + (size_t)(t + 1) * kstep;
;             const char* a2 = last ? nA : cA + (size_t)(t + 2) * kstep; const char* b2 = last ? nB : cB + (size_t)(t + 2) * kstep;
;             const char* a3 = a2 + kstep; const char* b3 = b2 + kstep;
;     ...
; #pragma unroll
;         for (int a = 0; a < 2; ++a)
; #pragma unroll
;             for (int b = 0; b < 2; ++b)
; #pragma unroll
;                 for (int m = 0; m < 4; ++m)
; #pragma unroll
;                     for (int n = 0; n < 2; ++n) acc[a][b][m][n] = (f32x4){0.f, 0.f, 0.f, 0.f};
.LBB0_666:
	s_ashr_i32 s73, s72, 31
	s_lshl_b64 s[16:17], s[72:73], 20
	v_readlane_b32 s58, v253, 59
	v_readlane_b32 s59, v253, 60
	s_add_u32 s74, s58, s16
	s_addc_u32 s75, s59, s17
	s_and_b64 s[16:17], s[4:5], exec
	s_cselect_b32 s46, s75, s23
	s_cselect_b32 s48, s74, s22
	s_ashr_i32 s71, s70, 31
	s_lshl_b64 s[16:17], s[70:71], 20
	s_add_u32 s76, s60, s16
	v_readlane_b32 s16, v255, 11
	s_addc_u32 s77, s16, s17
	s_and_b64 s[16:17], s[4:5], exec
	s_cselect_b32 s71, s77, s7
	s_cselect_b32 s73, s76, s6
	s_add_u32 s82, s22, 0x80080
	s_addc_u32 s83, s23, 0
	s_add_u32 s79, s6, 0x100
	v_mov_b32_e32 v0, 0
	s_addc_u32 s81, s7, 0
	s_mov_b32 s92, -2
	v_mov_b32_e32 v1, v0
	v_mov_b64_e32 v[2:3], v[0:1]
	v_mov_b64_e32 v[4:5], v[0:1]
	v_mov_b64_e32 v[6:7], v[0:1]
	v_mov_b64_e32 v[8:9], v[0:1]
	v_mov_b64_e32 v[10:11], v[0:1]
	v_mov_b64_e32 v[12:13], v[0:1]
	v_mov_b64_e32 v[14:15], v[0:1]
	v_mov_b64_e32 v[16:17], v[0:1]
	v_mov_b64_e32 v[18:19], v[0:1]
	v_mov_b64_e32 v[20:21], v[0:1]
	v_mov_b64_e32 v[22:23], v[0:1]
	v_mov_b64_e32 v[24:25], v[0:1]
	v_mov_b64_e32 v[26:27], v[0:1]
	v_mov_b64_e32 v[28:29], v[0:1]
	v_mov_b64_e32 v[30:31], v[0:1]
	v_mov_b64_e32 v[32:33], v[0:1]
	v_mov_b64_e32 v[34:35], v[0:1]
	v_mov_b64_e32 v[36:37], v[0:1]
	v_mov_b64_e32 v[38:39], v[0:1]
	v_mov_b64_e32 v[40:41], v[0:1]
	v_mov_b64_e32 v[42:43], v[0:1]
	v_mov_b64_e32 v[44:45], v[0:1]
	v_mov_b64_e32 v[46:47], v[0:1]
	v_mov_b64_e32 v[48:49], v[0:1]
	v_mov_b64_e32 v[50:51], v[0:1]
	v_mov_b64_e32 v[52:53], v[0:1]
	v_mov_b64_e32 v[54:55], v[0:1]
	v_mov_b64_e32 v[56:57], v[0:1]
	v_mov_b64_e32 v[58:59], v[0:1]
	v_mov_b64_e32 v[60:61], v[0:1]
	v_mov_b64_e32 v[62:63], v[0:1]
	v_mov_b64_e32 v[64:65], v[0:1]
	v_mov_b64_e32 v[66:67], v[0:1]
	v_mov_b64_e32 v[68:69], v[0:1]
	v_mov_b64_e32 v[70:71], v[0:1]
	v_mov_b64_e32 v[72:73], v[0:1]
	v_mov_b64_e32 v[74:75], v[0:1]
	v_mov_b64_e32 v[76:77], v[0:1]
	v_mov_b64_e32 v[78:79], v[0:1]
	v_mov_b64_e32 v[80:81], v[0:1]
	v_mov_b64_e32 v[82:83], v[0:1]
	v_mov_b64_e32 v[84:85], v[0:1]
	v_mov_b64_e32 v[86:87], v[0:1]
	v_mov_b64_e32 v[88:89], v[0:1]
	v_mov_b64_e32 v[90:91], v[0:1]
	v_mov_b64_e32 v[92:93], v[0:1]
	v_mov_b64_e32 v[94:95], v[0:1]
	v_mov_b64_e32 v[96:97], v[0:1]
	v_mov_b64_e32 v[98:99], v[0:1]
	v_mov_b64_e32 v[100:101], v[0:1]
	v_mov_b64_e32 v[102:103], v[0:1]
	v_mov_b64_e32 v[104:105], v[0:1]
	v_mov_b64_e32 v[106:107], v[0:1]
	v_mov_b64_e32 v[108:109], v[0:1]
	v_mov_b64_e32 v[110:111], v[0:1]
	v_mov_b64_e32 v[112:113], v[0:1]
	v_mov_b64_e32 v[114:115], v[0:1]
	v_mov_b64_e32 v[116:117], v[0:1]
	v_mov_b64_e32 v[118:119], v[0:1]
	v_mov_b64_e32 v[120:121], v[0:1]
	v_mov_b64_e32 v[122:123], v[0:1]
	v_mov_b64_e32 v[124:125], v[0:1]
	v_mov_b64_e32 v[126:127], v[0:1]

;     MI bool next(int i, Unit& u) const { return o.next(i, u); }
;     MI const char* aptr(const Unit& u) const { return (u.pn >= 8 && u.pn < 12) ? w + (size_t)u.pn * 256 * DM * 2 : hx + (size_t)u.pm * 256 * DM * 2; }
;     MI const char* bptr(const Unit& u) const { return (u.pn >= 8 && u.pn < 12) ? hx + (size_t)u.pm * 256 * DM * 2 : w + (size_t)u.pn * 256 * DM * 2; }
;     MI bool next(int i, Unit& u) const { return o.next(i, u); }
; template <bool PERM, class Epi, class Sched>
; __device__ __forceinline__ void gemm_phase(LAS unsigned char* lds, const int K, const Sched& S, const Epi& E, const int wid0) {
;     ...
;         const bool has_next = S.next(ui + 1, nxt);
;         const char* nA = has_next ? S.aptr(nxt) : cA; const char* nB = has_next ? S.bptr(nxt) : cB;
;         for (int t = 0; t < nt; t += 2) {
;             const bool last = (t == nt - 2);
;             const char* a1 = cA + (size_t)(t + 1) * kstep;
;             const char* a2 = last ? nA : cA + (size_t)(t + 2) * kstep; const char* b2 = last ? nB : cB + (size_t)(t + 2) * kstep;
;             const char* a3 = a2 + kstep; const char* b3 = b2 + kstep;
;     ...
; #pragma unroll
;         for (int a = 0; a < 2; ++a)
; #pragma unroll
;             for (int b = 0; b < 2; ++b)
; #pragma unroll
;                 for (int m = 0; m < 4; ++m)
; #pragma unroll
;                     for (int n = 0; n < 2; ++n) acc[a][b][m][n] = (f32x4){0.f, 0.f, 0.f, 0.f};
.LBB0_734:
	s_ashr_i32 s73, s72, 31
	s_lshl_b64 s[6:7], s[72:73], 20
	s_add_u32 s74, s90, s6
	s_addc_u32 s75, s91, s7
	s_and_b64 s[6:7], s[4:5], exec
	s_cselect_b32 s73, s75, s23
	s_cselect_b32 s79, s74, s22
	s_ashr_i32 s71, s70, 31
	s_lshl_b64 s[6:7], s[70:71], 20
	s_add_u32 s6, s60, s6
	v_readlane_b32 s16, v255, 13
	s_addc_u32 s7, s16, s7
	s_and_b64 s[16:17], s[4:5], exec
	s_cselect_b32 s71, s7, s77
	s_cselect_b32 s81, s6, s76
	s_add_u32 s82, s22, 0x80080
	s_addc_u32 s83, s23, 0
	s_add_u32 s92, s76, 0x100
	v_mov_b32_e32 v0, 0
	s_addc_u32 s93, s77, 0
	s_mov_b32 vcc_lo, -2
	v_mov_b32_e32 v1, v0
	v_mov_b64_e32 v[2:3], v[0:1]
	v_mov_b64_e32 v[4:5], v[0:1]
	v_mov_b64_e32 v[6:7], v[0:1]
	v_mov_b64_e32 v[8:9], v[0:1]
	v_mov_b64_e32 v[10:11], v[0:1]
	v_mov_b64_e32 v[12:13], v[0:1]
	v_mov_b64_e32 v[14:15], v[0:1]
	v_mov_b64_e32 v[16:17], v[0:1]
	v_mov_b64_e32 v[18:19], v[0:1]
	v_mov_b64_e32 v[20:21], v[0:1]
	v_mov_b64_e32 v[22:23], v[0:1]
	v_mov_b64_e32 v[24:25], v[0:1]
	v_mov_b64_e32 v[26:27], v[0:1]
	v_mov_b64_e32 v[28:29], v[0:1]
	v_mov_b64_e32 v[30:31], v[0:1]
	v_mov_b64_e32 v[32:33], v[0:1]
	v_mov_b64_e32 v[34:35], v[0:1]
	v_mov_b64_e32 v[36:37], v[0:1]
	v_mov_b64_e32 v[38:39], v[0:1]
	v_mov_b64_e32 v[40:41], v[0:1]
	v_mov_b64_e32 v[42:43], v[0:1]
	v_mov_b64_e32 v[44:45], v[0:1]
	v_mov_b64_e32 v[46:47], v[0:1]
	v_mov_b64_e32 v[48:49], v[0:1]
	v_mov_b64_e32 v[50:51], v[0:1]
	v_mov_b64_e32 v[52:53], v[0:1]
	v_mov_b64_e32 v[54:55], v[0:1]
	v_mov_b64_e32 v[56:57], v[0:1]
	v_mov_b64_e32 v[58:59], v[0:1]
	v_mov_b64_e32 v[60:61], v[0:1]
	v_mov_b64_e32 v[62:63], v[0:1]
	v_mov_b64_e32 v[64:65], v[0:1]
	v_mov_b64_e32 v[66:67], v[0:1]
	v_mov_b64_e32 v[68:69], v[0:1]
	v_mov_b64_e32 v[70:71], v[0:1]
	v_mov_b64_e32 v[72:73], v[0:1]
	v_mov_b64_e32 v[74:75], v[0:1]
	v_mov_b64_e32 v[76:77], v[0:1]
	v_mov_b64_e32 v[78:79], v[0:1]
	v_mov_b64_e32 v[80:81], v[0:1]
	v_mov_b64_e32 v[82:83], v[0:1]
	v_mov_b64_e32 v[84:85], v[0:1]
	v_mov_b64_e32 v[86:87], v[0:1]
	v_mov_b64_e32 v[88:89], v[0:1]
	v_mov_b64_e32 v[90:91], v[0:1]
	v_mov_b64_e32 v[92:93], v[0:1]
	v_mov_b64_e32 v[94:95], v[0:1]
	v_mov_b64_e32 v[96:97], v[0:1]
	v_mov_b64_e32 v[98:99], v[0:1]
	v_mov_b64_e32 v[100:101], v[0:1]
	v_mov_b64_e32 v[102:103], v[0:1]
	v_mov_b64_e32 v[104:105], v[0:1]
	v_mov_b64_e32 v[106:107], v[0:1]
	v_mov_b64_e32 v[108:109], v[0:1]
	v_mov_b64_e32 v[110:111], v[0:1]
	v_mov_b64_e32 v[128:129], v[0:1]
	v_mov_b64_e32 v[130:131], v[0:1]
	v_mov_b64_e32 v[132:133], v[0:1]
	v_mov_b64_e32 v[134:135], v[0:1]
	v_mov_b64_e32 v[136:137], v[0:1]
	v_mov_b64_e32 v[138:139], v[0:1]
	v_mov_b64_e32 v[140:141], v[0:1]
	v_mov_b64_e32 v[142:143], v[0:1]

;     MI bool next(int i, Unit& u) const { return o.next(i, u); }
;     MI const char* aptr(const Unit& u) const { return (u.pn >= 8 && u.pn < 12) ? w + (size_t)u.pn * 256 * DM * 2 : hx + (size_t)u.pm * 256 * DM * 2; }
;     MI const char* bptr(const Unit& u) const { return (u.pn >= 8 && u.pn < 12) ? hx + (size_t)u.pm * 256 * DM * 2 : w + (size_t)u.pn * 256 * DM * 2; }
;     MI bool next(int i, Unit& u) const { return o.next(i, u); }
; template <bool PERM, class Epi, class Sched>
; __device__ __forceinline__ void gemm_phase(LAS unsigned char* lds, const int K, const Sched& S, const Epi& E, const int wid0) {
;     ...
;         const bool has_next = S.next(ui + 1, nxt);
;         const char* nA = has_next ? S.aptr(nxt) : cA; const char* nB = has_next ? S.bptr(nxt) : cB;
;         for (int t = 0; t < nt; t += 2) {
;             const bool last = (t == nt - 2);
;             const char* a1 = cA + (size_t)(t + 1) * kstep;
;             const char* a2 = last ? nA : cA + (size_t)(t + 2) * kstep; const char* b2 = last ? nB : cB + (size_t)(t + 2) * kstep;
;             const char* a3 = a2 + kstep; const char* b3 = b2 + kstep;
;     ...
; #pragma unroll
;         for (int a = 0; a < 2; ++a)
; #pragma unroll
;             for (int b = 0; b < 2; ++b)
; #pragma unroll
;                 for (int m = 0; m < 4; ++m)
; #pragma unroll
;                     for (int n = 0; n < 2; ++n) acc[a][b][m][n] = (f32x4){0.f, 0.f, 0.f, 0.f};
.LBB0_865:
	s_ashr_i32 s75, s74, 31
	s_lshl_b64 s[16:17], s[74:75], 20
	s_add_u32 s76, s86, s16
	s_addc_u32 s77, s87, s17
	s_and_b64 s[16:17], s[4:5], exec
	s_cselect_b32 s75, s77, s23
	s_cselect_b32 s81, s76, s22
	s_ashr_i32 s73, s72, 31
	s_lshl_b64 s[16:17], s[72:73], 20
	v_readlane_b32 s58, v255, 18
	s_add_u32 s78, s58, s16
	v_readlane_b32 s16, v255, 19
	s_addc_u32 s79, s16, s17
	s_and_b64 s[16:17], s[4:5], exec
	s_cselect_b32 s73, s79, s7
	s_cselect_b32 s83, s78, s6
	s_add_u32 vcc_lo, s22, 0x80080
	s_addc_u32 vcc_hi, s23, 0
	s_add_u32 s92, s6, 0x100
	v_mov_b32_e32 v0, 0
	s_addc_u32 s93, s7, 0
	s_mov_b32 s16, -2
	v_mov_b32_e32 v1, v0
	v_mov_b64_e32 v[2:3], v[0:1]
	v_mov_b64_e32 v[4:5], v[0:1]
	v_mov_b64_e32 v[6:7], v[0:1]
	v_mov_b64_e32 v[8:9], v[0:1]
	v_mov_b64_e32 v[10:11], v[0:1]
	v_mov_b64_e32 v[12:13], v[0:1]
	v_mov_b64_e32 v[14:15], v[0:1]
	v_mov_b64_e32 v[16:17], v[0:1]
	v_mov_b64_e32 v[18:19], v[0:1]
	v_mov_b64_e32 v[20:21], v[0:1]
	v_mov_b64_e32 v[22:23], v[0:1]
	v_mov_b64_e32 v[24:25], v[0:1]
	v_mov_b64_e32 v[26:27], v[0:1]
	v_mov_b64_e32 v[28:29], v[0:1]
	v_mov_b64_e32 v[30:31], v[0:1]
	v_mov_b64_e32 v[32:33], v[0:1]
	v_mov_b64_e32 v[34:35], v[0:1]
	v_mov_b64_e32 v[36:37], v[0:1]
	v_mov_b64_e32 v[38:39], v[0:1]
	v_mov_b64_e32 v[40:41], v[0:1]
	v_mov_b64_e32 v[42:43], v[0:1]
	v_mov_b64_e32 v[44:45], v[0:1]
	v_mov_b64_e32 v[46:47], v[0:1]
	v_mov_b64_e32 v[48:49], v[0:1]
	v_mov_b64_e32 v[50:51], v[0:1]
	v_mov_b64_e32 v[52:53], v[0:1]
	v_mov_b64_e32 v[54:55], v[0:1]
	v_mov_b64_e32 v[56:57], v[0:1]
	v_mov_b64_e32 v[58:59], v[0:1]
	v_mov_b64_e32 v[60:61], v[0:1]
	v_mov_b64_e32 v[62:63], v[0:1]
	v_mov_b64_e32 v[64:65], v[0:1]
	v_mov_b64_e32 v[66:67], v[0:1]
	v_mov_b64_e32 v[68:69], v[0:1]
	v_mov_b64_e32 v[70:71], v[0:1]
	v_mov_b64_e32 v[72:73], v[0:1]
	v_mov_b64_e32 v[74:75], v[0:1]
	v_mov_b64_e32 v[76:77], v[0:1]
	v_mov_b64_e32 v[78:79], v[0:1]
	v_mov_b64_e32 v[80:81], v[0:1]
	v_mov_b64_e32 v[82:83], v[0:1]
	v_mov_b64_e32 v[84:85], v[0:1]
	v_mov_b64_e32 v[86:87], v[0:1]
	v_mov_b64_e32 v[88:89], v[0:1]
	v_mov_b64_e32 v[90:91], v[0:1]
	v_mov_b64_e32 v[92:93], v[0:1]
	v_mov_b64_e32 v[94:95], v[0:1]
	v_mov_b64_e32 v[96:97], v[0:1]
	v_mov_b64_e32 v[98:99], v[0:1]
	v_mov_b64_e32 v[100:101], v[0:1]
	v_mov_b64_e32 v[102:103], v[0:1]
	v_mov_b64_e32 v[104:105], v[0:1]
	v_mov_b64_e32 v[106:107], v[0:1]
	v_mov_b64_e32 v[108:109], v[0:1]
	v_mov_b64_e32 v[110:111], v[0:1]
	v_mov_b64_e32 v[112:113], v[0:1]
	v_mov_b64_e32 v[114:115], v[0:1]
	v_mov_b64_e32 v[116:117], v[0:1]
	v_mov_b64_e32 v[118:119], v[0:1]
	v_mov_b64_e32 v[120:121], v[0:1]
	v_mov_b64_e32 v[122:123], v[0:1]
	v_mov_b64_e32 v[124:125], v[0:1]
	v_mov_b64_e32 v[126:127], v[0:1]

;     MI bool next(int i, Unit& u) const { return o.next(i, u); }
;     MI const char* aptr(const Unit& u) const { return (u.pn >= 8 && u.pn < 12) ? w + (size_t)u.pn * 256 * DM * 2 : hx + (size_t)u.pm * 256 * DM * 2; }
;     MI const char* bptr(const Unit& u) const { return (u.pn >= 8 && u.pn < 12) ? hx + (size_t)u.pm * 256 * DM * 2 : w + (size_t)u.pn * 256 * DM * 2; }
;     MI bool next(int i, Unit& u) const { return o.next(i, u); }
; template <bool PERM, class Epi, class Sched>
; __device__ __forceinline__ void gemm_phase(LAS unsigned char* lds, const int K, const Sched& S, const Epi& E, const int wid0) {
;     ...
;         const bool has_next = S.next(ui + 1, nxt);
;         const char* nA = has_next ? S.aptr(nxt) : cA; const char* nB = has_next ? S.bptr(nxt) : cB;
;         for (int t = 0; t < nt; t += 2) {
;             const bool last = (t == nt - 2);
;             const char* a1 = cA + (size_t)(t + 1) * kstep;
;             const char* a2 = last ? nA : cA + (size_t)(t + 2) * kstep; const char* b2 = last ? nB : cB + (size_t)(t + 2) * kstep;
;             const char* a3 = a2 + kstep; const char* b3 = b2 + kstep;
;     ...
; #pragma unroll
;         for (int a = 0; a < 2; ++a)
; #pragma unroll
;             for (int b = 0; b < 2; ++b)
; #pragma unroll
;                 for (int m = 0; m < 4; ++m)
; #pragma unroll
;                     for (int n = 0; n < 2; ++n) acc[a][b][m][n] = (f32x4){0.f, 0.f, 0.f, 0.f};
.LBB0_933:
	s_ashr_i32 s69, s68, 31
	s_lshl_b64 s[16:17], s[68:69], 22
	s_add_u32 s70, s94, s16
	s_addc_u32 s71, s95, s17
	s_and_b64 s[16:17], s[4:5], exec
	s_cselect_b32 s69, s71, s23
	s_cselect_b32 s77, s70, s22
	s_ashr_i32 s25, s24, 31
	s_lshl_b64 s[16:17], s[24:25], 22
	v_readlane_b32 s25, v255, 20
	s_add_u32 s72, s25, s16
	v_readlane_b32 s16, v255, 21
	s_addc_u32 s73, s16, s17
	s_and_b64 s[16:17], s[4:5], exec
	s_cselect_b32 s25, s73, s81
	s_cselect_b32 s82, s72, s80
	s_add_u32 s78, s22, 0x200080
	s_addc_u32 s79, s23, 0
	s_add_u32 s83, s80, 0x100
	v_mov_b32_e32 v0, 0
	s_addc_u32 s92, s81, 0
	s_mov_b32 s16, -2
	v_mov_b32_e32 v1, v0
	v_mov_b64_e32 v[2:3], v[0:1]
	v_mov_b64_e32 v[4:5], v[0:1]
	v_mov_b64_e32 v[6:7], v[0:1]
	v_mov_b64_e32 v[8:9], v[0:1]
	v_mov_b64_e32 v[10:11], v[0:1]
	v_mov_b64_e32 v[12:13], v[0:1]
	v_mov_b64_e32 v[14:15], v[0:1]
	v_mov_b64_e32 v[16:17], v[0:1]
	v_mov_b64_e32 v[18:19], v[0:1]
	v_mov_b64_e32 v[20:21], v[0:1]
	v_mov_b64_e32 v[22:23], v[0:1]
	v_mov_b64_e32 v[24:25], v[0:1]
	v_mov_b64_e32 v[26:27], v[0:1]
	v_mov_b64_e32 v[28:29], v[0:1]
	v_mov_b64_e32 v[30:31], v[0:1]
	v_mov_b64_e32 v[32:33], v[0:1]
	v_mov_b64_e32 v[34:35], v[0:1]
	v_mov_b64_e32 v[36:37], v[0:1]
	v_mov_b64_e32 v[38:39], v[0:1]
	v_mov_b64_e32 v[40:41], v[0:1]
	v_mov_b64_e32 v[42:43], v[0:1]
	v_mov_b64_e32 v[44:45], v[0:1]
	v_mov_b64_e32 v[46:47], v[0:1]
	v_mov_b64_e32 v[48:49], v[0:1]
	v_mov_b64_e32 v[50:51], v[0:1]
	v_mov_b64_e32 v[52:53], v[0:1]
	v_mov_b64_e32 v[54:55], v[0:1]
	v_mov_b64_e32 v[60:61], v[0:1]
	v_mov_b64_e32 v[62:63], v[0:1]
	v_mov_b64_e32 v[64:65], v[0:1]
	v_mov_b64_e32 v[66:67], v[0:1]
	v_mov_b64_e32 v[68:69], v[0:1]
	v_mov_b64_e32 v[70:71], v[0:1]
	v_mov_b64_e32 v[72:73], v[0:1]
	v_mov_b64_e32 v[74:75], v[0:1]
	v_mov_b64_e32 v[76:77], v[0:1]
	v_mov_b64_e32 v[78:79], v[0:1]
	v_mov_b64_e32 v[80:81], v[0:1]
	v_mov_b64_e32 v[82:83], v[0:1]
	v_mov_b64_e32 v[84:85], v[0:1]
	v_mov_b64_e32 v[86:87], v[0:1]
	v_mov_b64_e32 v[88:89], v[0:1]
	v_mov_b64_e32 v[90:91], v[0:1]
	v_mov_b64_e32 v[92:93], v[0:1]
	v_mov_b64_e32 v[94:95], v[0:1]
	v_mov_b64_e32 v[96:97], v[0:1]
	v_mov_b64_e32 v[98:99], v[0:1]
	v_mov_b64_e32 v[100:101], v[0:1]
	v_mov_b64_e32 v[102:103], v[0:1]
	v_mov_b64_e32 v[104:105], v[0:1]
	v_mov_b64_e32 v[106:107], v[0:1]
	v_mov_b64_e32 v[116:117], v[0:1]
	v_mov_b64_e32 v[118:119], v[0:1]
	v_mov_b64_e32 v[124:125], v[0:1]
	v_mov_b64_e32 v[126:127], v[0:1]
	v_mov_b64_e32 v[128:129], v[0:1]
	v_mov_b64_e32 v[130:131], v[0:1]
	v_mov_b64_e32 v[132:133], v[0:1]
	v_mov_b64_e32 v[134:135], v[0:1]
	v_mov_b64_e32 v[136:137], v[0:1]
	v_mov_b64_e32 v[138:139], v[0:1]
	v_mov_b64_e32 v[140:141], v[0:1]
	v_mov_b64_e32 v[142:143], v[0:1]
